# attention steady steps: phase C transposed reads issued early inside phase B and the two accumulation chains run in read-issue order (plus the MFMA hoist and exp spread)
# speedup vs baseline: 1.0071x; 1.0071x over previous
.LBB0_974:
	v_add_u32_e32 v94, s44, v241
	ds_read_b128 v[82:85], v94
	ds_read_b128 v[198:201], v94 offset:512
	s_waitcnt lgkmcnt(12)
	v_mfma_f32_32x32x16_bf16 v[50:65], v[154:157], v[98:101], v[50:65]
	v_exp_f32_e32 v130, v130
	v_exp_f32_e32 v131, v131
	v_exp_f32_e32 v132, v132
	ds_read_b128 v[202:205], v94 offset:2048
	ds_read_b128 v[194:197], v94 offset:2560
	s_waitcnt lgkmcnt(12)
	v_mfma_f32_32x32x16_bf16 v[34:49], v[154:157], v[102:105], v[34:49]
	v_exp_f32_e32 v133, v133
	v_exp_f32_e32 v134, v134
	v_exp_f32_e32 v135, v135
	v_add_u32_e32 v102, s40, v228
	ds_read_b128 v[190:193], v94 offset:4096
	ds_read_b128 v[186:189], v94 offset:4608
	s_waitcnt lgkmcnt(12)
	v_mfma_f32_32x32x16_bf16 v[50:65], v[150:153], v[106:109], v[50:65]
	v_exp_f32_e32 v136, v136
	v_exp_f32_e32 v137, v137
	v_exp_f32_e32 v138, v138
	ds_read_b128 v[182:185], v94 offset:6144
	ds_read_b128 v[178:181], v94 offset:6656
	ds_read_b64_tr_b16 v[98:99],v102 offset:3072
	ds_read_b64_tr_b16 v[100:101],v102 offset:3584
	ds_read_b64_tr_b16 v[94:95],v102 offset:2048
	ds_read_b64_tr_b16 v[96:97],v102 offset:2560
	s_waitcnt lgkmcnt(15)
	v_mfma_f32_32x32x16_bf16 v[34:49], v[150:153], v[110:113], v[34:49]
	v_exp_f32_e32 v139, v139
	v_exp_f32_e32 v140, v140
	v_exp_f32_e32 v141, v141
	s_waitcnt lgkmcnt(14)
	v_mfma_f32_32x32x16_bf16 v[50:65], v[146:149], v[86:89], v[50:65]
	v_exp_f32_e32 v142, v142
	v_exp_f32_e32 v143, v143
	ds_read_b64_tr_b16 v[86:87],v102 offset:0
	ds_read_b64_tr_b16 v[88:89],v102 offset:512
	s_waitcnt lgkmcnt(14)
	v_mfma_f32_32x32x16_bf16 v[34:49], v[146:149], v[90:93], v[34:49]
	v_exp_f32_e32 v144, v144
	v_exp_f32_e32 v145, v145
	ds_read_b64_tr_b16 v[90:91],v102 offset:1024
	ds_read_b64_tr_b16 v[92:93],v102 offset:1536
	s_waitcnt lgkmcnt(6)
	v_mfma_f32_32x32x16_bf16 v[18:33], v[146:149], v[98:101], v[18:33]
	v_exp_f32_e32 v114, v114
	v_exp_f32_e32 v115, v115
	ds_read_b64_tr_b16 v[98:99],v102 offset:7168
	ds_read_b64_tr_b16 v[100:101],v102 offset:7680
	s_waitcnt lgkmcnt(6)
	v_mfma_f32_32x32x16_bf16 v[18:33], v[150:153], v[94:97], v[18:33]
	v_exp_f32_e32 v116, v116
	v_exp_f32_e32 v117, v117
	ds_read_b64_tr_b16 v[94:95],v102 offset:6144
	ds_read_b64_tr_b16 v[96:97],v102 offset:6656
	s_waitcnt lgkmcnt(6)
	v_mfma_f32_32x32x16_bf16 v[18:33], v[158:161], v[86:89], v[18:33]
	v_exp_f32_e32 v118, v118
	v_exp_f32_e32 v119, v119
	ds_read_b64_tr_b16 v[86:87],v102 offset:4096
	ds_read_b64_tr_b16 v[88:89],v102 offset:4608
	s_waitcnt lgkmcnt(6)
	v_mfma_f32_32x32x16_bf16 v[18:33], v[154:157], v[90:93], v[18:33]
	v_exp_f32_e32 v120, v120
	v_exp_f32_e32 v121, v121
	ds_read_b64_tr_b16 v[90:91],v102 offset:5120
	ds_read_b64_tr_b16 v[92:93],v102 offset:5632
	s_waitcnt lgkmcnt(6)
	v_mfma_f32_32x32x16_bf16 v[2:17], v[146:149], v[98:101], v[2:17]
	v_exp_f32_e32 v122, v122
	v_exp_f32_e32 v123, v123
	s_waitcnt vmcnt(3) lgkmcnt(0)
	s_barrier
	s_andn2_b64 vcc, exec, s[2:3]
	v_add_u32_e32 v229, s94, v243
	v_mfma_f32_32x32x16_bf16 v[2:17], v[150:153], v[94:97], v[2:17]
	v_exp_f32_e32 v124, v124
	v_exp_f32_e32 v125, v125
	v_mfma_f32_32x32x16_bf16 v[2:17], v[158:161], v[86:89], v[2:17]
	v_exp_f32_e32 v126, v126
	v_exp_f32_e32 v127, v127
	v_mfma_f32_32x32x16_bf16 v[2:17], v[154:157], v[90:93], v[2:17]
	v_exp_f32_e32 v128, v128
	v_exp_f32_e32 v129, v129
	s_cbranch_vccnz .LBB0_976
	s_waitcnt lgkmcnt(0)
	ds_read_b128 v[86:89], v229 offset:96
	ds_read_b128 v[90:93], v229 offset:64
	ds_read_b128 v[94:97], v229 offset:32
	ds_read_b128 v[98:101], v229
	s_waitcnt lgkmcnt(3)
	v_pk_mul_f32 v[62:63], v[62:63], v[86:87]
	s_waitcnt lgkmcnt(2)
	v_pk_mul_f32 v[58:59], v[58:59], v[90:91]
	s_waitcnt lgkmcnt(1)
	v_pk_mul_f32 v[54:55], v[54:55], v[94:95]
	v_pk_mul_f32 v[64:65], v[64:65], v[88:89]
	v_pk_mul_f32 v[60:61], v[60:61], v[92:93]
	v_pk_mul_f32 v[56:57], v[56:57], v[96:97]
	s_waitcnt lgkmcnt(0)
	v_pk_mul_f32 v[52:53], v[52:53], v[100:101]
	v_pk_mul_f32 v[50:51], v[50:51], v[98:99]
	v_pk_mul_f32 v[46:47], v[46:47], v[86:87]
	v_pk_mul_f32 v[42:43], v[42:43], v[90:91]
	v_pk_mul_f32 v[38:39], v[38:39], v[94:95]
	v_pk_mul_f32 v[48:49], v[48:49], v[88:89]
	v_pk_mul_f32 v[44:45], v[44:45], v[92:93]
	v_pk_mul_f32 v[40:41], v[40:41], v[96:97]
	v_pk_mul_f32 v[36:37], v[36:37], v[100:101]
	v_pk_mul_f32 v[34:35], v[34:35], v[98:99]
	v_pk_mul_f32 v[30:31], v[30:31], v[86:87]
	v_pk_mul_f32 v[26:27], v[26:27], v[90:91]
	v_pk_mul_f32 v[22:23], v[22:23], v[94:95]
	v_pk_mul_f32 v[32:33], v[32:33], v[88:89]
	v_pk_mul_f32 v[28:29], v[28:29], v[92:93]
	v_pk_mul_f32 v[24:25], v[24:25], v[96:97]
	v_pk_mul_f32 v[20:21], v[20:21], v[100:101]
	v_pk_mul_f32 v[18:19], v[18:19], v[98:99]
	v_pk_mul_f32 v[14:15], v[14:15], v[86:87]
	v_pk_mul_f32 v[10:11], v[10:11], v[90:91]
	v_pk_mul_f32 v[6:7], v[6:7], v[94:95]
	v_pk_mul_f32 v[16:17], v[16:17], v[88:89]
	v_pk_mul_f32 v[12:13], v[12:13], v[92:93]
	v_pk_mul_f32 v[8:9], v[8:9], v[96:97]
	v_pk_mul_f32 v[4:5], v[4:5], v[100:101]
	v_pk_mul_f32 v[2:3], v[2:3], v[98:99]

.LBB0_977:
	v_add_u32_e32 v126, s40, v241
	ds_read_b128 v[206:209], v126
	ds_read_b128 v[202:205], v126 offset:512
	s_waitcnt lgkmcnt(12)
	v_mfma_f32_32x32x16_bf16 v[50:65], v[154:157], v[130:133], v[50:65]
	v_exp_f32_e32 v98, v98
	v_exp_f32_e32 v99, v99
	v_exp_f32_e32 v100, v100
	ds_read_b128 v[198:201], v126 offset:2048
	ds_read_b128 v[194:197], v126 offset:2560
	s_waitcnt lgkmcnt(12)
	v_mfma_f32_32x32x16_bf16 v[34:49], v[154:157], v[134:137], v[34:49]
	v_exp_f32_e32 v101, v101
	v_exp_f32_e32 v102, v102
	v_exp_f32_e32 v103, v103
	v_add_u32_e32 v130, s45, v228
	ds_read_b128 v[190:193], v126 offset:4096
	ds_read_b128 v[186:189], v126 offset:4608
	s_waitcnt lgkmcnt(12)
	v_mfma_f32_32x32x16_bf16 v[50:65], v[150:153], v[138:141], v[50:65]
	v_exp_f32_e32 v104, v104
	v_exp_f32_e32 v105, v105
	v_exp_f32_e32 v106, v106
	ds_read_b128 v[182:185], v126 offset:6144
	ds_read_b128 v[178:181], v126 offset:6656
	ds_read_b64_tr_b16 v[126:127],v130 offset:3072
	ds_read_b64_tr_b16 v[128:129],v130 offset:3584
	s_waitcnt lgkmcnt(14)
	v_mfma_f32_32x32x16_bf16 v[34:49], v[150:153], v[114:117], v[34:49]
	v_exp_f32_e32 v107, v107
	v_exp_f32_e32 v108, v108
	v_exp_f32_e32 v109, v109
	ds_read_b64_tr_b16 v[114:115],v130 offset:0
	ds_read_b64_tr_b16 v[116:117],v130 offset:512
	s_waitcnt lgkmcnt(14)
	v_mfma_f32_32x32x16_bf16 v[50:65], v[146:149], v[118:121], v[50:65]
	v_exp_f32_e32 v110, v110
	v_exp_f32_e32 v111, v111
	ds_read_b64_tr_b16 v[118:119],v130 offset:1024
	ds_read_b64_tr_b16 v[120:121],v130 offset:1536
	s_waitcnt lgkmcnt(14)
	v_mfma_f32_32x32x16_bf16 v[34:49], v[146:149], v[122:125], v[34:49]
	v_exp_f32_e32 v112, v112
	v_exp_f32_e32 v113, v113
	ds_read_b64_tr_b16 v[122:123],v130 offset:2048
	ds_read_b64_tr_b16 v[124:125],v130 offset:2560
	s_waitcnt lgkmcnt(6)
	v_mfma_f32_32x32x16_bf16 v[18:33], v[146:149], v[126:129], v[18:33]
	v_exp_f32_e32 v82, v82
	v_exp_f32_e32 v83, v83
	ds_read_b64_tr_b16 v[126:127],v130 offset:7168
	ds_read_b64_tr_b16 v[128:129],v130 offset:7680
	s_waitcnt lgkmcnt(6)
	v_mfma_f32_32x32x16_bf16 v[18:33], v[158:161], v[114:117], v[18:33]
	v_exp_f32_e32 v84, v84
	v_exp_f32_e32 v85, v85
	ds_read_b64_tr_b16 v[114:115],v130 offset:4096
	ds_read_b64_tr_b16 v[116:117],v130 offset:4608
	s_waitcnt lgkmcnt(6)
	v_mfma_f32_32x32x16_bf16 v[18:33], v[154:157], v[118:121], v[18:33]
	v_exp_f32_e32 v86, v86
	v_exp_f32_e32 v87, v87
	ds_read_b64_tr_b16 v[118:119],v130 offset:5120
	ds_read_b64_tr_b16 v[120:121],v130 offset:5632
	s_waitcnt lgkmcnt(6)
	v_mfma_f32_32x32x16_bf16 v[18:33], v[150:153], v[122:125], v[18:33]
	v_exp_f32_e32 v88, v88
	v_exp_f32_e32 v89, v89
	ds_read_b64_tr_b16 v[122:123],v130 offset:6144
	ds_read_b64_tr_b16 v[124:125],v130 offset:6656
	s_waitcnt lgkmcnt(6)
	v_mfma_f32_32x32x16_bf16 v[2:17], v[146:149], v[126:129], v[2:17]
	v_exp_f32_e32 v90, v90
	v_exp_f32_e32 v91, v91
	s_waitcnt vmcnt(3) lgkmcnt(0)
	s_barrier
	s_andn2_b64 vcc, exec, s[2:3]
	v_mfma_f32_32x32x16_bf16 v[2:17], v[158:161], v[114:117], v[2:17]
	v_exp_f32_e32 v92, v92
	v_exp_f32_e32 v93, v93
	v_mfma_f32_32x32x16_bf16 v[2:17], v[154:157], v[118:121], v[2:17]
	v_exp_f32_e32 v94, v94
	v_exp_f32_e32 v95, v95
	v_mfma_f32_32x32x16_bf16 v[2:17], v[150:153], v[122:125], v[2:17]
	v_exp_f32_e32 v96, v96
	v_exp_f32_e32 v97, v97
	s_cbranch_vccnz .LBB0_979
	s_waitcnt lgkmcnt(0)
	ds_read_b128 v[114:117], v229 offset:96
	ds_read_b128 v[118:121], v229 offset:64
	ds_read_b128 v[122:125], v229 offset:32
	ds_read_b128 v[126:129], v229
	s_waitcnt lgkmcnt(3)
	v_pk_mul_f32 v[62:63], v[62:63], v[114:115]
	s_waitcnt lgkmcnt(2)
	v_pk_mul_f32 v[58:59], v[58:59], v[118:119]
	s_waitcnt lgkmcnt(1)
	v_pk_mul_f32 v[54:55], v[54:55], v[122:123]
	v_pk_mul_f32 v[64:65], v[64:65], v[116:117]
	v_pk_mul_f32 v[60:61], v[60:61], v[120:121]
	v_pk_mul_f32 v[56:57], v[56:57], v[124:125]
	s_waitcnt lgkmcnt(0)
	v_pk_mul_f32 v[52:53], v[52:53], v[128:129]
	v_pk_mul_f32 v[50:51], v[50:51], v[126:127]
	v_pk_mul_f32 v[46:47], v[46:47], v[114:115]
	v_pk_mul_f32 v[42:43], v[42:43], v[118:119]
	v_pk_mul_f32 v[38:39], v[38:39], v[122:123]
	v_pk_mul_f32 v[48:49], v[48:49], v[116:117]
	v_pk_mul_f32 v[44:45], v[44:45], v[120:121]
	v_pk_mul_f32 v[40:41], v[40:41], v[124:125]
	v_pk_mul_f32 v[36:37], v[36:37], v[128:129]
	v_pk_mul_f32 v[34:35], v[34:35], v[126:127]
	v_pk_mul_f32 v[30:31], v[30:31], v[114:115]
	v_pk_mul_f32 v[26:27], v[26:27], v[118:119]
	v_pk_mul_f32 v[22:23], v[22:23], v[122:123]
	v_pk_mul_f32 v[32:33], v[32:33], v[116:117]
	v_pk_mul_f32 v[28:29], v[28:29], v[120:121]
	v_pk_mul_f32 v[24:25], v[24:25], v[124:125]
	v_pk_mul_f32 v[20:21], v[20:21], v[128:129]
	v_pk_mul_f32 v[18:19], v[18:19], v[126:127]
	v_pk_mul_f32 v[14:15], v[14:15], v[114:115]
	v_pk_mul_f32 v[10:11], v[10:11], v[118:119]
	v_pk_mul_f32 v[6:7], v[6:7], v[122:123]
	v_pk_mul_f32 v[16:17], v[16:17], v[116:117]
	v_pk_mul_f32 v[12:13], v[12:13], v[120:121]
	v_pk_mul_f32 v[8:9], v[8:9], v[124:125]
	v_pk_mul_f32 v[4:5], v[4:5], v[128:129]
	v_pk_mul_f32 v[2:3], v[2:3], v[126:127]

.LBB0_1080:
	v_add_u32_e32 v94, s43, v241
	ds_read_b128 v[82:85], v94
	ds_read_b128 v[198:201], v94 offset:512
	s_waitcnt lgkmcnt(12)
	v_mfma_f32_32x32x16_bf16 v[50:65], v[162:165], v[98:101], v[50:65]
	v_exp_f32_e32 v130, v130
	v_exp_f32_e32 v131, v131
	v_exp_f32_e32 v132, v132
	ds_read_b128 v[202:205], v94 offset:2048
	ds_read_b128 v[194:197], v94 offset:2560
	s_waitcnt lgkmcnt(12)
	v_mfma_f32_32x32x16_bf16 v[34:49], v[162:165], v[102:105], v[34:49]
	v_exp_f32_e32 v133, v133
	v_exp_f32_e32 v134, v134
	v_exp_f32_e32 v135, v135
	v_add_u32_e32 v102, s40, v228
	ds_read_b128 v[190:193], v94 offset:4096
	ds_read_b128 v[186:189], v94 offset:4608
	s_waitcnt lgkmcnt(12)
	v_mfma_f32_32x32x16_bf16 v[50:65], v[158:161], v[106:109], v[50:65]
	v_exp_f32_e32 v136, v136
	v_exp_f32_e32 v137, v137
	v_exp_f32_e32 v138, v138
	ds_read_b128 v[182:185], v94 offset:6144
	ds_read_b128 v[178:181], v94 offset:6656
	ds_read_b64_tr_b16 v[98:99],v102 offset:3072
	ds_read_b64_tr_b16 v[100:101],v102 offset:3584
	ds_read_b64_tr_b16 v[94:95],v102 offset:2048
	ds_read_b64_tr_b16 v[96:97],v102 offset:2560
	s_waitcnt lgkmcnt(15)
	v_mfma_f32_32x32x16_bf16 v[34:49], v[158:161], v[110:113], v[34:49]
	v_exp_f32_e32 v139, v139
	v_exp_f32_e32 v140, v140
	v_exp_f32_e32 v141, v141
	s_waitcnt lgkmcnt(14)
	v_mfma_f32_32x32x16_bf16 v[50:65], v[154:157], v[86:89], v[50:65]
	v_exp_f32_e32 v142, v142
	v_exp_f32_e32 v143, v143
	ds_read_b64_tr_b16 v[86:87],v102 offset:0
	ds_read_b64_tr_b16 v[88:89],v102 offset:512
	s_waitcnt lgkmcnt(14)
	v_mfma_f32_32x32x16_bf16 v[34:49], v[154:157], v[90:93], v[34:49]
	v_exp_f32_e32 v144, v144
	v_exp_f32_e32 v145, v145
	ds_read_b64_tr_b16 v[90:91],v102 offset:1024
	ds_read_b64_tr_b16 v[92:93],v102 offset:1536
	s_waitcnt lgkmcnt(6)
	v_mfma_f32_32x32x16_bf16 v[18:33], v[154:157], v[98:101], v[18:33]
	v_exp_f32_e32 v114, v114
	v_exp_f32_e32 v115, v115
	ds_read_b64_tr_b16 v[98:99],v102 offset:7168
	ds_read_b64_tr_b16 v[100:101],v102 offset:7680
	s_waitcnt lgkmcnt(6)
	v_mfma_f32_32x32x16_bf16 v[18:33], v[158:161], v[94:97], v[18:33]
	v_exp_f32_e32 v116, v116
	v_exp_f32_e32 v117, v117
	ds_read_b64_tr_b16 v[94:95],v102 offset:6144
	ds_read_b64_tr_b16 v[96:97],v102 offset:6656
	s_waitcnt lgkmcnt(6)
	v_mfma_f32_32x32x16_bf16 v[18:33], v[166:169], v[86:89], v[18:33]
	v_exp_f32_e32 v118, v118
	v_exp_f32_e32 v119, v119
	ds_read_b64_tr_b16 v[86:87],v102 offset:4096
	ds_read_b64_tr_b16 v[88:89],v102 offset:4608
	s_waitcnt lgkmcnt(6)
	v_mfma_f32_32x32x16_bf16 v[18:33], v[162:165], v[90:93], v[18:33]
	v_exp_f32_e32 v120, v120
	v_exp_f32_e32 v121, v121
	ds_read_b64_tr_b16 v[90:91],v102 offset:5120
	ds_read_b64_tr_b16 v[92:93],v102 offset:5632
	s_waitcnt lgkmcnt(6)
	v_mfma_f32_32x32x16_bf16 v[2:17], v[154:157], v[98:101], v[2:17]
	v_exp_f32_e32 v122, v122
	v_exp_f32_e32 v123, v123
	s_waitcnt vmcnt(3) lgkmcnt(0)
	s_barrier
	s_andn2_b64 vcc, exec, s[2:3]
	v_add_u32_e32 v229, s39, v243
	v_mfma_f32_32x32x16_bf16 v[2:17], v[158:161], v[94:97], v[2:17]
	v_exp_f32_e32 v124, v124
	v_exp_f32_e32 v125, v125
	v_mfma_f32_32x32x16_bf16 v[2:17], v[166:169], v[86:89], v[2:17]
	v_exp_f32_e32 v126, v126
	v_exp_f32_e32 v127, v127
	v_mfma_f32_32x32x16_bf16 v[2:17], v[162:165], v[90:93], v[2:17]
	v_exp_f32_e32 v128, v128
	v_exp_f32_e32 v129, v129
	s_cbranch_vccnz .LBB0_1082
	s_waitcnt lgkmcnt(0)
	ds_read_b128 v[86:89], v229 offset:96
	ds_read_b128 v[90:93], v229 offset:64
	ds_read_b128 v[94:97], v229 offset:32
	ds_read_b128 v[98:101], v229
	s_waitcnt lgkmcnt(3)
	v_pk_mul_f32 v[62:63], v[62:63], v[86:87]
	s_waitcnt lgkmcnt(2)
	v_pk_mul_f32 v[58:59], v[58:59], v[90:91]
	s_waitcnt lgkmcnt(1)
	v_pk_mul_f32 v[54:55], v[54:55], v[94:95]
	v_pk_mul_f32 v[64:65], v[64:65], v[88:89]
	v_pk_mul_f32 v[60:61], v[60:61], v[92:93]
	v_pk_mul_f32 v[56:57], v[56:57], v[96:97]
	s_waitcnt lgkmcnt(0)
	v_pk_mul_f32 v[52:53], v[52:53], v[100:101]
	v_pk_mul_f32 v[50:51], v[50:51], v[98:99]
	v_pk_mul_f32 v[46:47], v[46:47], v[86:87]
	v_pk_mul_f32 v[42:43], v[42:43], v[90:91]
	v_pk_mul_f32 v[38:39], v[38:39], v[94:95]
	v_pk_mul_f32 v[48:49], v[48:49], v[88:89]
	v_pk_mul_f32 v[44:45], v[44:45], v[92:93]
	v_pk_mul_f32 v[40:41], v[40:41], v[96:97]
	v_pk_mul_f32 v[36:37], v[36:37], v[100:101]
	v_pk_mul_f32 v[34:35], v[34:35], v[98:99]
	v_pk_mul_f32 v[30:31], v[30:31], v[86:87]
	v_pk_mul_f32 v[26:27], v[26:27], v[90:91]
	v_pk_mul_f32 v[22:23], v[22:23], v[94:95]
	v_pk_mul_f32 v[32:33], v[32:33], v[88:89]
	v_pk_mul_f32 v[28:29], v[28:29], v[92:93]
	v_pk_mul_f32 v[24:25], v[24:25], v[96:97]
	v_pk_mul_f32 v[20:21], v[20:21], v[100:101]
	v_pk_mul_f32 v[18:19], v[18:19], v[98:99]
	v_pk_mul_f32 v[14:15], v[14:15], v[86:87]
	v_pk_mul_f32 v[10:11], v[10:11], v[90:91]
	v_pk_mul_f32 v[6:7], v[6:7], v[94:95]
	v_pk_mul_f32 v[16:17], v[16:17], v[88:89]
	v_pk_mul_f32 v[12:13], v[12:13], v[92:93]
	v_pk_mul_f32 v[8:9], v[8:9], v[96:97]
	v_pk_mul_f32 v[4:5], v[4:5], v[100:101]
	v_pk_mul_f32 v[2:3], v[2:3], v[98:99]

.LBB0_1083:
	v_add_u32_e32 v126, s40, v241
	ds_read_b128 v[206:209], v126
	ds_read_b128 v[198:201], v126 offset:512
	s_waitcnt lgkmcnt(12)
	v_mfma_f32_32x32x16_bf16 v[50:65], v[162:165], v[130:133], v[50:65]
	v_exp_f32_e32 v98, v98
	v_exp_f32_e32 v99, v99
	v_exp_f32_e32 v100, v100
	ds_read_b128 v[202:205], v126 offset:2048
	ds_read_b128 v[194:197], v126 offset:2560
	s_waitcnt lgkmcnt(12)
	v_mfma_f32_32x32x16_bf16 v[34:49], v[162:165], v[134:137], v[34:49]
	v_exp_f32_e32 v101, v101
	v_exp_f32_e32 v102, v102
	v_exp_f32_e32 v103, v103
	v_add_u32_e32 v130, s47, v228
	ds_read_b128 v[190:193], v126 offset:4096
	ds_read_b128 v[186:189], v126 offset:4608
	s_waitcnt lgkmcnt(12)
	v_mfma_f32_32x32x16_bf16 v[50:65], v[158:161], v[138:141], v[50:65]
	v_exp_f32_e32 v104, v104
	v_exp_f32_e32 v105, v105
	v_exp_f32_e32 v106, v106
	ds_read_b128 v[182:185], v126 offset:6144
	ds_read_b128 v[178:181], v126 offset:6656
	ds_read_b64_tr_b16 v[126:127],v130 offset:3072
	ds_read_b64_tr_b16 v[128:129],v130 offset:3584
	s_waitcnt lgkmcnt(14)
	v_mfma_f32_32x32x16_bf16 v[34:49], v[158:161], v[114:117], v[34:49]
	v_exp_f32_e32 v107, v107
	v_exp_f32_e32 v108, v108
	v_exp_f32_e32 v109, v109
	ds_read_b64_tr_b16 v[114:115],v130 offset:0
	ds_read_b64_tr_b16 v[116:117],v130 offset:512
	s_waitcnt lgkmcnt(14)
	v_mfma_f32_32x32x16_bf16 v[50:65], v[154:157], v[118:121], v[50:65]
	v_exp_f32_e32 v110, v110
	v_exp_f32_e32 v111, v111
	ds_read_b64_tr_b16 v[118:119],v130 offset:1024
	ds_read_b64_tr_b16 v[120:121],v130 offset:1536
	s_waitcnt lgkmcnt(14)
	v_mfma_f32_32x32x16_bf16 v[34:49], v[154:157], v[122:125], v[34:49]
	v_exp_f32_e32 v112, v112
	v_exp_f32_e32 v113, v113
	ds_read_b64_tr_b16 v[122:123],v130 offset:2048
	ds_read_b64_tr_b16 v[124:125],v130 offset:2560
	s_waitcnt lgkmcnt(6)
	v_mfma_f32_32x32x16_bf16 v[18:33], v[154:157], v[126:129], v[18:33]
	v_exp_f32_e32 v82, v82
	v_exp_f32_e32 v83, v83
	ds_read_b64_tr_b16 v[126:127],v130 offset:7168
	ds_read_b64_tr_b16 v[128:129],v130 offset:7680
	s_waitcnt lgkmcnt(6)
	v_mfma_f32_32x32x16_bf16 v[18:33], v[166:169], v[114:117], v[18:33]
	v_exp_f32_e32 v84, v84
	v_exp_f32_e32 v85, v85
	ds_read_b64_tr_b16 v[114:115],v130 offset:4096
	ds_read_b64_tr_b16 v[116:117],v130 offset:4608
	s_waitcnt lgkmcnt(6)
	v_mfma_f32_32x32x16_bf16 v[18:33], v[162:165], v[118:121], v[18:33]
	v_exp_f32_e32 v86, v86
	v_exp_f32_e32 v87, v87
	ds_read_b64_tr_b16 v[118:119],v130 offset:5120
	ds_read_b64_tr_b16 v[120:121],v130 offset:5632
	s_waitcnt lgkmcnt(6)
	v_mfma_f32_32x32x16_bf16 v[18:33], v[158:161], v[122:125], v[18:33]
	v_exp_f32_e32 v88, v88
	v_exp_f32_e32 v89, v89
	ds_read_b64_tr_b16 v[122:123],v130 offset:6144
	ds_read_b64_tr_b16 v[124:125],v130 offset:6656
	s_waitcnt lgkmcnt(6)
	v_mfma_f32_32x32x16_bf16 v[2:17], v[154:157], v[126:129], v[2:17]
	v_exp_f32_e32 v90, v90
	v_exp_f32_e32 v91, v91
	s_waitcnt vmcnt(3) lgkmcnt(0)
	s_barrier
	s_andn2_b64 vcc, exec, s[2:3]
	v_mfma_f32_32x32x16_bf16 v[2:17], v[166:169], v[114:117], v[2:17]
	v_exp_f32_e32 v92, v92
	v_exp_f32_e32 v93, v93
	v_mfma_f32_32x32x16_bf16 v[2:17], v[162:165], v[118:121], v[2:17]
	v_exp_f32_e32 v94, v94
	v_exp_f32_e32 v95, v95
	v_mfma_f32_32x32x16_bf16 v[2:17], v[158:161], v[122:125], v[2:17]
	v_exp_f32_e32 v96, v96
	v_exp_f32_e32 v97, v97
	s_cbranch_vccnz .LBB0_1085
	s_waitcnt lgkmcnt(0)
	ds_read_b128 v[114:117], v229 offset:96
	ds_read_b128 v[118:121], v229 offset:64
	ds_read_b128 v[122:125], v229 offset:32
	ds_read_b128 v[126:129], v229
	s_waitcnt lgkmcnt(3)
	v_pk_mul_f32 v[62:63], v[62:63], v[114:115]
	s_waitcnt lgkmcnt(2)
	v_pk_mul_f32 v[58:59], v[58:59], v[118:119]
	s_waitcnt lgkmcnt(1)
	v_pk_mul_f32 v[54:55], v[54:55], v[122:123]
	v_pk_mul_f32 v[64:65], v[64:65], v[116:117]
	v_pk_mul_f32 v[60:61], v[60:61], v[120:121]
	v_pk_mul_f32 v[56:57], v[56:57], v[124:125]
	s_waitcnt lgkmcnt(0)
	v_pk_mul_f32 v[52:53], v[52:53], v[128:129]
	v_pk_mul_f32 v[50:51], v[50:51], v[126:127]
	v_pk_mul_f32 v[46:47], v[46:47], v[114:115]
	v_pk_mul_f32 v[42:43], v[42:43], v[118:119]
	v_pk_mul_f32 v[38:39], v[38:39], v[122:123]
	v_pk_mul_f32 v[48:49], v[48:49], v[116:117]
	v_pk_mul_f32 v[44:45], v[44:45], v[120:121]
	v_pk_mul_f32 v[40:41], v[40:41], v[124:125]
	v_pk_mul_f32 v[36:37], v[36:37], v[128:129]
	v_pk_mul_f32 v[34:35], v[34:35], v[126:127]
	v_pk_mul_f32 v[30:31], v[30:31], v[114:115]
	v_pk_mul_f32 v[26:27], v[26:27], v[118:119]
	v_pk_mul_f32 v[22:23], v[22:23], v[122:123]
	v_pk_mul_f32 v[32:33], v[32:33], v[116:117]
	v_pk_mul_f32 v[28:29], v[28:29], v[120:121]
	v_pk_mul_f32 v[24:25], v[24:25], v[124:125]
	v_pk_mul_f32 v[20:21], v[20:21], v[128:129]
	v_pk_mul_f32 v[18:19], v[18:19], v[126:127]
	v_pk_mul_f32 v[14:15], v[14:15], v[114:115]
	v_pk_mul_f32 v[10:11], v[10:11], v[118:119]
	v_pk_mul_f32 v[6:7], v[6:7], v[122:123]
	v_pk_mul_f32 v[16:17], v[16:17], v[116:117]
	v_pk_mul_f32 v[12:13], v[12:13], v[120:121]
	v_pk_mul_f32 v[8:9], v[8:9], v[124:125]
	v_pk_mul_f32 v[4:5], v[4:5], v[128:129]
	v_pk_mul_f32 v[2:3], v[2:3], v[126:127]
